# attention: ticket requested at band-loop entry, picked up at the final step; wave 0 touches next unit Q rows and bias row into L2
# speedup vs baseline: 1.0288x; 1.0029x over previous
.LBB0_128:
	s_or_b64 exec, exec, s[4:5]
	s_waitcnt lgkmcnt(0)
	ds_read_b128 v[32:35], v216 offset:49280
	ds_read_b128 v[36:39], v216 offset:49312
	s_lshl_b64 s[2:3], s[2:3], 12
	v_readlane_b32 s4, v252, 37
	s_add_u32 s5, s4, s2
	s_waitcnt lgkmcnt(1)
	v_rcp_f32_e32 v40, v32
	v_readlane_b32 s2, v252, 38
	s_addc_u32 s6, s2, s3
	s_lshl_b64 s[2:3], s[14:15], 1
	v_readlane_b32 s4, v252, 35
	v_rcp_f32_e32 v41, v33
	s_add_u32 s7, s4, s2
	v_readlane_b32 s2, v252, 36
	s_addc_u32 s14, s2, s3
	s_lshl_b32 s2, s13, 12
	s_add_i32 s4, s2, 0
	v_lshlrev_b32_e32 v48, 1, v211
	v_lshlrev_b32_e32 v49, 9, v212
	v_mul_f32_e32 v0, v0, v40
	v_add3_u32 v48, s4, v48, v49
	v_cvt_pk_bf16_f32 v0, v0, s0
	v_rcp_f32_e32 v42, v34
	v_rcp_f32_e32 v43, v35
	s_waitcnt lgkmcnt(0)
	v_rcp_f32_e32 v44, v36
	ds_read_b128 v[32:35], v216 offset:49344
	v_rcp_f32_e32 v45, v37
	v_rcp_f32_e32 v46, v38
	v_rcp_f32_e32 v47, v39
	ds_read_b128 v[36:39], v216 offset:49376
	ds_write_b16 v48, v0 offset:51264
	v_mul_f32_e32 v0, v17, v41
	v_cvt_pk_bf16_f32 v0, v0, s0
	ds_write_b16 v48, v0 offset:51328
	v_mul_f32_e32 v0, v1, v41
	v_cvt_pk_bf16_f32 v0, v0, s0
	ds_write_b16 v48, v0 offset:51392
	v_mul_f32_e32 v0, v18, v42
	v_cvt_pk_bf16_f32 v0, v0, s0
	ds_write_b16 v48, v0 offset:51456
	v_mul_f32_e32 v0, v2, v42
	v_cvt_pk_bf16_f32 v0, v0, s0
	ds_write_b16 v48, v0 offset:51520
	v_mul_f32_e32 v0, v19, v43
	v_cvt_pk_bf16_f32 v0, v0, s0
	ds_write_b16 v48, v0 offset:51584
	v_mul_f32_e32 v0, v3, v43
	v_cvt_pk_bf16_f32 v0, v0, s0
	ds_write_b16 v48, v0 offset:51648
	v_mul_f32_e32 v0, v20, v44
	v_cvt_pk_bf16_f32 v0, v0, s0
	ds_write_b16 v48, v0 offset:52224
	v_mul_f32_e32 v0, v4, v44
	v_cvt_pk_bf16_f32 v0, v0, s0
	ds_write_b16 v48, v0 offset:52288
	v_mul_f32_e32 v0, v21, v45
	v_cvt_pk_bf16_f32 v0, v0, s0
	ds_write_b16 v48, v0 offset:52352
	v_mul_f32_e32 v0, v5, v45
	v_cvt_pk_bf16_f32 v0, v0, s0
	ds_write_b16 v48, v0 offset:52416
	v_mul_f32_e32 v0, v22, v46
	v_cvt_pk_bf16_f32 v0, v0, s0
	ds_write_b16 v48, v0 offset:52480
	v_mul_f32_e32 v0, v6, v46
	v_cvt_pk_bf16_f32 v0, v0, s0
	s_waitcnt lgkmcnt(13)
	v_rcp_f32_e32 v32, v32
	ds_write_b16 v48, v0 offset:52544
	v_mul_f32_e32 v0, v23, v47
	v_cvt_pk_bf16_f32 v0, v0, s0
	ds_write_b16 v48, v0 offset:52608
	v_mul_f32_e32 v0, v7, v47
	v_cvt_pk_bf16_f32 v0, v0, s0
	v_rcp_f32_e32 v33, v33
	ds_write_b16 v48, v0 offset:52672
	v_mul_f32_e32 v0, v24, v32
	v_cvt_pk_bf16_f32 v0, v0, s0
	ds_write_b16 v48, v0 offset:53248
	v_mul_f32_e32 v0, v8, v32
	v_cvt_pk_bf16_f32 v0, v0, s0
	v_rcp_f32_e32 v34, v34
	ds_write_b16 v48, v0 offset:53312
	v_mul_f32_e32 v0, v25, v33
	v_cvt_pk_bf16_f32 v0, v0, s0
	ds_write_b16 v48, v0 offset:53376
	v_mul_f32_e32 v0, v9, v33
	v_cvt_pk_bf16_f32 v0, v0, s0
	v_rcp_f32_e32 v35, v35
	ds_write_b16 v48, v0 offset:53440
	v_mul_f32_e32 v0, v26, v34
	v_cvt_pk_bf16_f32 v0, v0, s0
	ds_write_b16 v48, v0 offset:53504
	v_mul_f32_e32 v0, v10, v34
	v_cvt_pk_bf16_f32 v0, v0, s0
	s_waitcnt lgkmcnt(14)
	v_rcp_f32_e32 v36, v36
	ds_write_b16 v48, v0 offset:53568
	v_mul_f32_e32 v0, v27, v35
	v_cvt_pk_bf16_f32 v0, v0, s0
	ds_write_b16 v48, v0 offset:53632
	v_mul_f32_e32 v0, v11, v35
	v_cvt_pk_bf16_f32 v0, v0, s0
	v_rcp_f32_e32 v37, v37
	ds_write_b16 v48, v0 offset:53696
	v_mul_f32_e32 v0, v28, v36
	v_cvt_pk_bf16_f32 v0, v0, s0
	ds_write_b16 v48, v0 offset:54272
	v_mul_f32_e32 v0, v12, v36
	v_cvt_pk_bf16_f32 v0, v0, s0
	v_rcp_f32_e32 v38, v38
	ds_write_b16 v48, v0 offset:54336
	v_mul_f32_e32 v0, v29, v37
	v_cvt_pk_bf16_f32 v0, v0, s0
	ds_write_b16 v48, v0 offset:54400
	v_mul_f32_e32 v0, v13, v37
	v_cvt_pk_bf16_f32 v0, v0, s0
	v_rcp_f32_e32 v39, v39
	ds_write_b16 v48, v0 offset:54464
	v_mul_f32_e32 v0, v30, v38
	v_cvt_pk_bf16_f32 v0, v0, s0
	ds_write_b16 v48, v0 offset:54528
	v_mul_f32_e32 v0, v14, v38
	v_cvt_pk_bf16_f32 v0, v0, s0
	ds_write_b16 v48, v0 offset:54592
	v_mul_f32_e32 v0, v31, v39
	v_cvt_pk_bf16_f32 v0, v0, s0
	ds_write_b16 v48, v0 offset:54656
	v_mul_f32_e32 v0, v15, v39
	s_add_u32 s2, s5, s12
	v_mul_f32_e32 v16, v16, v40
	v_cvt_pk_bf16_f32 v0, v0, s0
	s_addc_u32 s3, s6, 0
	v_cvt_pk_bf16_f32 v16, v16, s0
	ds_write_b16 v48, v0 offset:54720
	s_add_u32 s6, s7, s12
	v_lshlrev_b32_e32 v0, 1, v210
	ds_write_b16 v48, v16 offset:51200
	s_addc_u32 s7, s14, 0
	v_lshrrev_b32_e32 v24, 3, v197
	v_and_b32_e32 v16, 0x70, v0
	v_mov_b32_e32 v17, v193
	v_lshl_add_u64 v[18:19], s[6:7], 0, v[16:17]
	v_lshlrev_b32_e32 v0, 11, v24
	v_mov_b32_e32 v1, v193
	s_waitcnt lgkmcnt(0)
	s_cmp_lg_u32 s13, 0
	s_cbranch_scc1 .Ltk_skipB
	s_cmp_eq_u32 s101, 2
	s_cbranch_scc1 .Ltk_skipB
	s_waitcnt vmcnt(0)
	v_readfirstlane_b32 s32, v250
	s_nop 3
	s_add_i32 s32, s32, s65
.Ltk_skipB:
	v_lshl_add_u64 v[0:1], v[18:19], 0, v[0:1]
	global_load_dwordx4 v[0:3], v[0:1], off
	v_or_b32_e32 v25, 8, v24
	v_lshlrev_b32_e32 v4, 11, v25
	v_mov_b32_e32 v5, v193
	v_lshl_add_u64 v[4:5], v[18:19], 0, v[4:5]
	global_load_dwordx4 v[4:7], v[4:5], off
	v_or_b32_e32 v26, 16, v24
	v_lshlrev_b32_e32 v8, 11, v26
	v_mov_b32_e32 v9, v193
	v_lshl_add_u64 v[8:9], v[18:19], 0, v[8:9]
	global_load_dwordx4 v[8:11], v[8:9], off
	v_add_u32_e32 v27, s4, v16
	v_lshl_add_u32 v12, v24, 7, v27
	ds_read_b128 v[12:15], v12 offset:51200
	v_lshl_add_u64 v[20:21], s[2:3], 0, v[16:17]
	v_or_b32_e32 v28, 24, v24
	s_waitcnt lgkmcnt(0)
	v_lshlrev_b32_e32 v16, 16, v12
	v_and_b32_e32 v17, 0xffff0000, v12
	v_lshlrev_b32_e32 v12, 16, v13
	v_and_b32_e32 v13, 0xffff0000, v13
	s_waitcnt vmcnt(2)
	v_lshlrev_b32_e32 v22, 16, v0
	v_and_b32_e32 v23, 0xffff0000, v0
	v_pk_mul_f32 v[16:17], v[16:17], v[22:23]
	v_lshlrev_b32_e32 v22, 16, v2
	v_cvt_pk_bf16_f32 v0, v16, v17
	v_lshlrev_b32_e32 v16, 16, v1
	v_and_b32_e32 v17, 0xffff0000, v1
	v_pk_mul_f32 v[12:13], v[12:13], v[16:17]
	v_lshlrev_b32_e32 v16, 11, v28
	v_mov_b32_e32 v17, v193
	v_lshl_add_u64 v[16:17], v[18:19], 0, v[16:17]
	global_load_dwordx4 v[16:19], v[16:17], off
	v_cvt_pk_bf16_f32 v1, v12, v13
	v_lshlrev_b32_e32 v12, 16, v14
	v_and_b32_e32 v13, 0xffff0000, v14
	v_and_b32_e32 v23, 0xffff0000, v2
	v_pk_mul_f32 v[12:13], v[12:13], v[22:23]
	v_lshlrev_b32_e32 v14, 16, v3
	v_cvt_pk_bf16_f32 v2, v12, v13
	v_lshlrev_b32_e32 v12, 16, v15
	v_and_b32_e32 v13, 0xffff0000, v15
	v_and_b32_e32 v15, 0xffff0000, v3
	v_pk_mul_f32 v[12:13], v[12:13], v[14:15]
	v_lshlrev_b32_e32 v22, 12, v24
	v_cvt_pk_bf16_f32 v3, v12, v13
	v_lshl_add_u32 v12, v25, 7, v27
	ds_read_b128 v[12:15], v12 offset:51200
	v_mov_b32_e32 v23, v193
	v_lshl_add_u64 v[22:23], v[20:21], 0, v[22:23]
	global_store_dwordx4 v[22:23], v[0:3], off
	s_waitcnt lgkmcnt(0)
	s_nop 0
	v_lshlrev_b32_e32 v0, 16, v12
	v_and_b32_e32 v1, 0xffff0000, v12
	s_waitcnt vmcnt(3)
	v_lshlrev_b32_e32 v2, 16, v4
	v_and_b32_e32 v3, 0xffff0000, v4
	v_pk_mul_f32 v[0:1], v[0:1], v[2:3]
	v_lshlrev_b32_e32 v2, 16, v13
	v_and_b32_e32 v3, 0xffff0000, v13
	v_lshlrev_b32_e32 v4, 16, v5
	v_and_b32_e32 v5, 0xffff0000, v5
	v_pk_mul_f32 v[2:3], v[2:3], v[4:5]
	v_cvt_pk_bf16_f32 v0, v0, v1
	v_cvt_pk_bf16_f32 v1, v2, v3
	v_lshlrev_b32_e32 v2, 16, v14
	v_and_b32_e32 v3, 0xffff0000, v14
	v_lshlrev_b32_e32 v4, 16, v6
	v_and_b32_e32 v5, 0xffff0000, v6
	v_pk_mul_f32 v[2:3], v[2:3], v[4:5]
	v_lshlrev_b32_e32 v4, 16, v15
	v_and_b32_e32 v5, 0xffff0000, v15
	v_lshlrev_b32_e32 v6, 16, v7
	v_and_b32_e32 v7, 0xffff0000, v7
	v_pk_mul_f32 v[4:5], v[4:5], v[6:7]
	v_cvt_pk_bf16_f32 v2, v2, v3
	v_cvt_pk_bf16_f32 v3, v4, v5
	v_lshl_add_u32 v4, v26, 7, v27
	ds_read_b128 v[4:7], v4 offset:51200
	v_lshlrev_b32_e32 v12, 12, v25
	v_mov_b32_e32 v13, v193
	v_lshl_add_u64 v[12:13], v[20:21], 0, v[12:13]
	global_store_dwordx4 v[12:13], v[0:3], off
	s_waitcnt lgkmcnt(0)
	s_nop 0
	v_lshlrev_b32_e32 v0, 16, v4
	v_and_b32_e32 v1, 0xffff0000, v4
	s_waitcnt vmcnt(3)
	v_lshlrev_b32_e32 v2, 16, v8
	v_and_b32_e32 v3, 0xffff0000, v8
	v_pk_mul_f32 v[0:1], v[0:1], v[2:3]
	v_lshlrev_b32_e32 v2, 16, v5
	v_and_b32_e32 v3, 0xffff0000, v5
	v_lshlrev_b32_e32 v4, 16, v9
	v_and_b32_e32 v5, 0xffff0000, v9
	v_pk_mul_f32 v[2:3], v[2:3], v[4:5]
	v_cvt_pk_bf16_f32 v0, v0, v1
	v_cvt_pk_bf16_f32 v1, v2, v3
	v_lshlrev_b32_e32 v2, 16, v6
	v_and_b32_e32 v3, 0xffff0000, v6
	v_lshlrev_b32_e32 v4, 16, v10
	v_and_b32_e32 v5, 0xffff0000, v10
	v_pk_mul_f32 v[2:3], v[2:3], v[4:5]
	v_lshlrev_b32_e32 v4, 16, v7
	v_and_b32_e32 v5, 0xffff0000, v7
	v_lshlrev_b32_e32 v6, 16, v11
	v_and_b32_e32 v7, 0xffff0000, v11
	v_pk_mul_f32 v[4:5], v[4:5], v[6:7]
	v_cvt_pk_bf16_f32 v2, v2, v3
	v_cvt_pk_bf16_f32 v3, v4, v5
	v_lshl_add_u32 v4, v28, 7, v27
	ds_read_b128 v[4:7], v4 offset:51200
	v_lshlrev_b32_e32 v8, 12, v26
	v_mov_b32_e32 v9, v193
	v_lshl_add_u64 v[8:9], v[20:21], 0, v[8:9]
	global_store_dwordx4 v[8:9], v[0:3], off
	s_waitcnt lgkmcnt(0)
	s_nop 0
	v_lshlrev_b32_e32 v0, 16, v4
	v_and_b32_e32 v1, 0xffff0000, v4
	s_waitcnt vmcnt(3)
	v_lshlrev_b32_e32 v2, 16, v16
	v_and_b32_e32 v3, 0xffff0000, v16
	v_pk_mul_f32 v[0:1], v[0:1], v[2:3]
	v_lshlrev_b32_e32 v2, 16, v5
	v_and_b32_e32 v3, 0xffff0000, v5
	v_lshlrev_b32_e32 v4, 16, v17
	v_and_b32_e32 v5, 0xffff0000, v17
	v_pk_mul_f32 v[2:3], v[2:3], v[4:5]
	v_cvt_pk_bf16_f32 v0, v0, v1
	v_cvt_pk_bf16_f32 v1, v2, v3
	v_lshlrev_b32_e32 v2, 16, v6
	v_and_b32_e32 v3, 0xffff0000, v6
	v_lshlrev_b32_e32 v4, 16, v18
	v_and_b32_e32 v5, 0xffff0000, v18
	v_pk_mul_f32 v[2:3], v[2:3], v[4:5]
	v_lshlrev_b32_e32 v4, 16, v7
	v_and_b32_e32 v5, 0xffff0000, v7
	v_lshlrev_b32_e32 v6, 16, v19
	v_and_b32_e32 v7, 0xffff0000, v19
	v_pk_mul_f32 v[4:5], v[4:5], v[6:7]
	v_cvt_pk_bf16_f32 v2, v2, v3
	v_cvt_pk_bf16_f32 v3, v4, v5
	v_lshlrev_b32_e32 v4, 12, v28
	v_mov_b32_e32 v5, v193
	v_lshl_add_u64 v[4:5], v[20:21], 0, v[4:5]
	global_store_dwordx4 v[4:5], v[0:3], off
	s_cmp_lg_u32 s13, 0
	s_cbranch_scc1 .Ltk_skip1
	s_mov_b64 s[6:7], exec
	s_mov_b64 exec, 1
	v_mov_b32_e32 v96, s32
	v_mov_b32_e32 v97, s68
	ds_write_b32 v97, v96
	s_mov_b64 exec, s[6:7]

.LBB0_166:
	s_mov_b32 s101, 0
	s_cmp_lg_u32 s13, 0
	s_cbranch_scc1 .Ltk_a0
	s_mov_b64 exec, 1
	v_mov_b32_e32 v250, 1
	global_atomic_add v250, v193, v250, s[8:9] sc0
	s_mov_b64 exec, -1

.LBB0_167:
	s_cmp_lg_u32 s13, 0
	s_cbranch_scc1 .Ltk_skipF
	s_cmp_lg_u32 s101, 1
	s_cbranch_scc1 .Ltk_skipF
	s_waitcnt vmcnt(0)
	v_readfirstlane_b32 s32, v250
	s_nop 3
	s_add_i32 s32, s32, s65
	s_mov_b32 s101, 2
	s_cmpk_gt_i32 s32, 0x3ff
	s_cbranch_scc1 .Ltk_skipF
	s_and_b32 s100, s32, 63
	s_lshr_b32 vcc_hi, s100, 4
	s_lshl_b32 vcc_hi, vcc_hi, 12
	s_lshr_b32 vcc_lo, s32, 6
	s_sub_i32 vcc_lo, 15, vcc_lo
	s_lshl_b32 vcc_lo, vcc_lo, 8
	s_add_i32 vcc_hi, vcc_hi, vcc_lo
	s_lshl_b32 vcc_hi, vcc_hi, 11
	s_and_b32 vcc_lo, s100, 15
	s_lshl_b32 vcc_lo, vcc_lo, 7
	s_add_i32 vcc_hi, vcc_hi, vcc_lo
	s_lshl_b32 s100, s100, 14
	v_lshlrev_b32_e32 v240, 11, v244
	v_readlane_b32 vcc_lo, v252, 23
	s_nop 3
	s_add_u32 vcc_lo, vcc_lo, vcc_hi
	v_readlane_b32 vcc_hi, v252, 24
	s_nop 3
	s_addc_u32 vcc_hi, vcc_hi, 0
	global_load_dword v242, v240, vcc
	s_add_u32 vcc_lo, vcc_lo, 0x20000
	s_addc_u32 vcc_hi, vcc_hi, 0
	global_load_dword v242, v240, vcc
	s_add_u32 vcc_lo, vcc_lo, 0x20000
	s_addc_u32 vcc_hi, vcc_hi, 0
	global_load_dword v242, v240, vcc
	s_add_u32 vcc_lo, vcc_lo, 0x20000
	s_addc_u32 vcc_hi, vcc_hi, 0
	global_load_dword v242, v240, vcc
	v_readlane_b32 vcc_lo, v252, 30
	v_readlane_b32 vcc_hi, v252, 31
	v_lshlrev_b32_e32 v240, 7, v244
	s_nop 3
	s_add_u32 vcc_lo, vcc_lo, s100
	s_addc_u32 vcc_hi, vcc_hi, 0
	global_load_dword v242, v240, vcc
	v_add_u32_e32 v240, 0x2000, v240
	s_nop 0
	global_load_dword v242, v240, vcc

.LBB0_173:
	s_mov_b32 s101, 1
	s_cmp_lg_u32 s13, 0
	s_cbranch_scc1 .Ltk_a1
	s_mov_b64 exec, 1
	v_mov_b32_e32 v250, 1
	global_atomic_add v250, v193, v250, s[8:9] sc0
	s_mov_b64 exec, -1

.LBB0_227:
	v_mov_b32_e32 v240, 0x6000
	v_mov_b32_e32 v242, 0x30000
	s_mov_b64 s[0:1], 0

	.amdhsa_kernel _Z14fwd_megakernel4Args
		.amdhsa_group_segment_fixed_size 0
		.amdhsa_private_segment_fixed_size 0
		.amdhsa_kernarg_size 384
		.amdhsa_user_sgpr_count 2
		.amdhsa_user_sgpr_dispatch_ptr 0
		.amdhsa_user_sgpr_queue_ptr 0
		.amdhsa_user_sgpr_kernarg_segment_ptr 1
		.amdhsa_user_sgpr_dispatch_id 0
		.amdhsa_user_sgpr_kernarg_preload_length 0
		.amdhsa_user_sgpr_kernarg_preload_offset 0
		.amdhsa_user_sgpr_private_segment_size 0
		.amdhsa_uses_dynamic_stack 0
		.amdhsa_enable_private_segment 0
		.amdhsa_system_sgpr_workgroup_id_x 1
		.amdhsa_system_sgpr_workgroup_id_y 0
		.amdhsa_system_sgpr_workgroup_id_z 0
		.amdhsa_system_sgpr_workgroup_info 0
		.amdhsa_system_vgpr_workitem_id 2
		.amdhsa_next_free_vgpr 256
		.amdhsa_next_free_sgpr 102
		.amdhsa_accum_offset 256
		.amdhsa_reserve_vcc 1
		.amdhsa_float_round_mode_32 0
		.amdhsa_float_round_mode_16_64 0
		.amdhsa_float_denorm_mode_32 3
		.amdhsa_float_denorm_mode_16_64 3
		.amdhsa_dx10_clamp 1
		.amdhsa_ieee_mode 1
		.amdhsa_fp16_overflow 0
		.amdhsa_tg_split 0
		.amdhsa_exception_fp_ieee_invalid_op 0
		.amdhsa_exception_fp_denorm_src 0
		.amdhsa_exception_fp_ieee_div_zero 0
		.amdhsa_exception_fp_ieee_overflow 0
		.amdhsa_exception_fp_ieee_underflow 0
		.amdhsa_exception_fp_ieee_inexact 0
		.amdhsa_exception_int_div_zero 0
	.end_amdhsa_kernel

amdhsa.kernels:
  - .agpr_count:     0
    .args:
      - .offset:         0
        .size:           128
        .value_kind:     by_value
      - .offset:         128
        .size:           4
        .value_kind:     hidden_block_count_x
      - .offset:         132
        .size:           4
        .value_kind:     hidden_block_count_y
      - .offset:         136
        .size:           4
        .value_kind:     hidden_block_count_z
      - .offset:         140
        .size:           2
        .value_kind:     hidden_group_size_x
      - .offset:         142
        .size:           2
        .value_kind:     hidden_group_size_y
      - .offset:         144
        .size:           2
        .value_kind:     hidden_group_size_z
      - .offset:         146
        .size:           2
        .value_kind:     hidden_remainder_x
      - .offset:         148
        .size:           2
        .value_kind:     hidden_remainder_y
      - .offset:         150
        .size:           2
        .value_kind:     hidden_remainder_z
      - .offset:         168
        .size:           8
        .value_kind:     hidden_global_offset_x
      - .offset:         176
        .size:           8
        .value_kind:     hidden_global_offset_y
      - .offset:         184
        .size:           8
        .value_kind:     hidden_global_offset_z
      - .offset:         192
        .size:           2
        .value_kind:     hidden_grid_dims
      - .offset:         216
        .size:           8
        .value_kind:     hidden_multigrid_sync_arg
      - .offset:         248
        .size:           4
        .value_kind:     hidden_dynamic_lds_size
    .group_segment_fixed_size: 0
    .kernarg_segment_align: 8
    .kernarg_segment_size: 384
    .language:       OpenCL C
    .language_version:
      - 2
      - 0
    .max_flat_workgroup_size: 512
    .name:           _Z14fwd_megakernel4Args
    .private_segment_fixed_size: 0
    .sgpr_count:     108
    .sgpr_spill_count: 291
    .symbol:         _Z14fwd_megakernel4Args.kd
    .uniform_work_group_size: 1
    .uses_dynamic_stack: false
    .vgpr_count:     256
    .vgpr_spill_count: 0
    .wavefront_size: 64
